# v22 + differential-attention unit epilogue: the 16 norm-gain loads issued together with counted waits (12 of them were serialized one round trip each)
# speedup vs baseline: 1.0048x; 1.0048x over previous
; __device__ __forceinline__ float bf_lo(unsigned w) { return __uint_as_float(w << 16); }
; __device__ __forceinline__ float bf_hi(unsigned w) { return __uint_as_float(w & 0xffff0000u); }
; __global__ void __launch_bounds__(512, 2) mega(Args a) {
;     ...
;                         l1 += __shfl_xor(l1, 32); const float il1 = lam / l1; float ss = 0.f;
; #pragma unroll
;                         for (int db = 0; db < 4; ++db)
; #pragma unroll
;                             for (int r = 0; r < 16; r += 2) { const float d0 = bf_lo(o0p[db][r >> 1]) - il1 * o1[db][r], d1 = bf_hi(o0p[db][r >> 1]) - il1 * o1[db][r + 1]; o1[db][r] = d0; o1[db][r + 1] = d1; ss += d0 * d0 + d1 * d1; }
.LBB0_137:
	ds_bpermute_b32 v0, v174, v224
	v_readlane_b32 s7, v251, 10
	v_and_b32_e32 v7, 0xffff0000, v169
	v_mov_b32_e32 v9, v18
	v_mov_b32_e32 v18, v17
	s_waitcnt lgkmcnt(0)
	v_add_f32_e32 v0, v224, v0
	v_div_scale_f32 v1, s[4:5], v0, v0, s7
	v_rcp_f32_e32 v2, v1
	v_mov_b32_e32 v8, v16
	v_and_b32_e32 v15, 0xffff0000, v163
	v_and_b32_e32 v14, 0xffff0000, v162
	v_fma_f32 v3, -v1, v2, 1.0
	v_fmac_f32_e32 v2, v3, v2
	v_div_scale_f32 v3, vcc, s7, v0, s7
	v_mul_f32_e32 v4, v3, v2
	v_fma_f32 v6, -v1, v4, v3
	v_fmac_f32_e32 v4, v6, v2
	v_fma_f32 v1, -v1, v4, v3
	v_div_fmas_f32 v1, v1, v2, v4
	v_div_fixup_f32 v0, v1, v0, s7
	v_lshlrev_b32_e32 v1, 16, v217
	v_lshlrev_b32_e32 v2, 16, v216
	v_fma_f32 v4, -v0, v64, v1
	v_and_b32_e32 v1, 0xffff0000, v217
	v_fma_f32 v11, -v0, v66, v2
	v_and_b32_e32 v2, 0xffff0000, v216
	v_fma_f32 v90, -v0, v65, v1
	v_fma_f32 v91, -v0, v67, v2
	v_mul_f32_e32 v1, v90, v90
	v_mul_f32_e32 v2, v91, v91
	v_fmac_f32_e32 v1, v4, v4
	v_fmac_f32_e32 v2, v11, v11
	v_add_f32_e32 v1, v1, v2
	v_lshlrev_b32_e32 v2, 16, v215
	v_fma_f32 v86, -v0, v68, v2
	v_and_b32_e32 v2, 0xffff0000, v215
	v_fma_f32 v87, -v0, v69, v2
	v_mul_f32_e32 v2, v87, v87
	v_fmac_f32_e32 v2, v86, v86
	v_add_f32_e32 v1, v1, v2
	v_lshlrev_b32_e32 v2, 16, v214
	v_fma_f32 v88, -v0, v70, v2
	v_and_b32_e32 v2, 0xffff0000, v214
	v_fma_f32 v89, -v0, v71, v2
	v_mul_f32_e32 v2, v89, v89
	v_fmac_f32_e32 v2, v88, v88
	v_add_f32_e32 v1, v1, v2
	v_lshlrev_b32_e32 v2, 16, v213
	v_fma_f32 v82, -v0, v72, v2
	v_and_b32_e32 v2, 0xffff0000, v213
	v_fma_f32 v83, -v0, v73, v2
	v_mul_f32_e32 v2, v83, v83
	v_fmac_f32_e32 v2, v82, v82
	v_add_f32_e32 v1, v1, v2
	v_lshlrev_b32_e32 v2, 16, v212
	v_fma_f32 v84, -v0, v74, v2
	v_and_b32_e32 v2, 0xffff0000, v212
	v_fma_f32 v85, -v0, v75, v2
	v_mul_f32_e32 v2, v85, v85
	v_fmac_f32_e32 v2, v84, v84
	v_add_f32_e32 v1, v1, v2
	v_lshlrev_b32_e32 v2, 16, v211
	v_fma_f32 v80, -v0, v76, v2
	v_and_b32_e32 v2, 0xffff0000, v211
	v_fma_f32 v81, -v0, v77, v2
	v_mul_f32_e32 v2, v81, v81
	v_fmac_f32_e32 v2, v80, v80
	v_add_f32_e32 v1, v1, v2
	v_lshlrev_b32_e32 v2, 16, v210
	v_fma_f32 v78, -v0, v78, v2
	v_and_b32_e32 v2, 0xffff0000, v210
	v_fma_f32 v79, -v0, v79, v2
	v_mul_f32_e32 v2, v79, v79
	v_fmac_f32_e32 v2, v78, v78
	v_add_f32_e32 v1, v1, v2
	v_lshlrev_b32_e32 v2, 16, v209
	v_fma_f32 v74, -v0, v48, v2
	v_and_b32_e32 v2, 0xffff0000, v209
	v_fma_f32 v75, -v0, v49, v2
	v_mul_f32_e32 v2, v75, v75
	v_fmac_f32_e32 v2, v74, v74
	v_add_f32_e32 v1, v1, v2
	v_lshlrev_b32_e32 v2, 16, v208
	v_fma_f32 v76, -v0, v50, v2
	v_and_b32_e32 v2, 0xffff0000, v208
	v_fma_f32 v77, -v0, v51, v2
	v_mul_f32_e32 v2, v77, v77
	v_fmac_f32_e32 v2, v76, v76
	v_add_f32_e32 v1, v1, v2
	v_lshlrev_b32_e32 v2, 16, v207
	v_fma_f32 v52, -v0, v52, v2
	v_and_b32_e32 v2, 0xffff0000, v207
	v_fma_f32 v71, -v0, v53, v2
	v_mul_f32_e32 v2, v71, v71
	v_fmac_f32_e32 v2, v52, v52
	v_add_f32_e32 v1, v1, v2
	v_lshlrev_b32_e32 v2, 16, v206
	v_fma_f32 v72, -v0, v54, v2
	v_and_b32_e32 v2, 0xffff0000, v206
	v_fma_f32 v73, -v0, v55, v2
	v_mul_f32_e32 v2, v73, v73
	v_fmac_f32_e32 v2, v72, v72
	v_add_f32_e32 v1, v1, v2
	v_lshlrev_b32_e32 v2, 16, v205
	v_fma_f32 v50, -v0, v56, v2
	v_and_b32_e32 v2, 0xffff0000, v205
	v_fma_f32 v53, -v0, v57, v2
	v_mul_f32_e32 v2, v53, v53
	v_fmac_f32_e32 v2, v50, v50
	v_add_f32_e32 v1, v1, v2
	v_lshlrev_b32_e32 v2, 16, v204
	v_fma_f32 v69, -v0, v58, v2
	v_and_b32_e32 v2, 0xffff0000, v204
	v_fma_f32 v70, -v0, v59, v2
	v_mul_f32_e32 v2, v70, v70
	v_fmac_f32_e32 v2, v69, v69
	v_add_f32_e32 v1, v1, v2
	v_lshlrev_b32_e32 v2, 16, v181
	v_fma_f32 v59, -v0, v60, v2
	v_and_b32_e32 v2, 0xffff0000, v181
	v_fma_f32 v60, -v0, v61, v2
	v_mul_f32_e32 v2, v60, v60
	v_fmac_f32_e32 v2, v59, v59
	v_add_f32_e32 v1, v1, v2
	v_lshlrev_b32_e32 v2, 16, v180
	v_fma_f32 v67, -v0, v62, v2
	v_and_b32_e32 v2, 0xffff0000, v180
	v_fma_f32 v68, -v0, v63, v2
	v_mul_f32_e32 v2, v68, v68
	v_fmac_f32_e32 v2, v67, v67
	v_add_f32_e32 v1, v1, v2
	v_lshlrev_b32_e32 v2, 16, v179
	v_fma_f32 v63, -v0, v32, v2
	v_and_b32_e32 v2, 0xffff0000, v179
	v_fma_f32 v64, -v0, v33, v2
	v_mul_f32_e32 v2, v64, v64
	v_fmac_f32_e32 v2, v63, v63
	v_add_f32_e32 v1, v1, v2
	v_lshlrev_b32_e32 v2, 16, v178
	v_fma_f32 v65, -v0, v34, v2
	v_and_b32_e32 v2, 0xffff0000, v178
	v_fma_f32 v66, -v0, v35, v2
	v_mul_f32_e32 v2, v66, v66
	v_fmac_f32_e32 v2, v65, v65
	v_add_f32_e32 v1, v1, v2
	v_lshlrev_b32_e32 v2, 16, v177
	v_fma_f32 v55, -v0, v36, v2
	v_and_b32_e32 v2, 0xffff0000, v177
	v_fma_f32 v56, -v0, v37, v2
	v_mul_f32_e32 v2, v56, v56
	v_fmac_f32_e32 v2, v55, v55
	v_add_f32_e32 v1, v1, v2
	v_lshlrev_b32_e32 v2, 16, v176
	v_fma_f32 v57, -v0, v38, v2
	v_and_b32_e32 v2, 0xffff0000, v176
	v_fma_f32 v58, -v0, v39, v2
	v_mul_f32_e32 v2, v58, v58
	v_fmac_f32_e32 v2, v57, v57
	v_add_f32_e32 v1, v1, v2
	v_lshlrev_b32_e32 v2, 16, v173
	v_fma_f32 v48, -v0, v40, v2
	v_and_b32_e32 v2, 0xffff0000, v173
	v_fma_f32 v49, -v0, v41, v2
	v_mul_f32_e32 v2, v49, v49
	v_fmac_f32_e32 v2, v48, v48
	v_add_f32_e32 v1, v1, v2
	v_lshlrev_b32_e32 v2, 16, v172
	v_fma_f32 v51, -v0, v42, v2
	v_and_b32_e32 v2, 0xffff0000, v172
	v_fma_f32 v54, -v0, v43, v2
	v_mul_f32_e32 v2, v54, v54
	v_fmac_f32_e32 v2, v51, v51
	v_add_f32_e32 v1, v1, v2
	v_lshlrev_b32_e32 v2, 16, v171
	v_fma_f32 v43, -v0, v44, v2
	v_and_b32_e32 v2, 0xffff0000, v171
	v_fma_f32 v44, -v0, v45, v2
	v_mul_f32_e32 v2, v44, v44
	v_fmac_f32_e32 v2, v43, v43
	v_add_f32_e32 v1, v1, v2
	v_lshlrev_b32_e32 v2, 16, v170
	v_fma_f32 v45, -v0, v46, v2
	v_and_b32_e32 v2, 0xffff0000, v170
	v_fma_f32 v46, -v0, v47, v2
	v_mul_f32_e32 v2, v46, v46
	v_fmac_f32_e32 v2, v45, v45
	v_add_f32_e32 v1, v1, v2
	v_and_b32_e32 v6, 0xffff0000, v168
; __device__ __forceinline__ float bf_lo(unsigned w) { return __uint_as_float(w << 16); }
; __device__ __forceinline__ float bf_hi(unsigned w) { return __uint_as_float(w & 0xffff0000u); }
; __global__ void __launch_bounds__(512, 2) mega(Args a) {
;     ...
;                             for (int r = 0; r < 16; r += 2) { const float d0 = bf_lo(o0p[db][r >> 1]) - il1 * o1[db][r], d1 = bf_hi(o0p[db][r >> 1]) - il1 * o1[db][r + 1]; o1[db][r] = d0; o1[db][r + 1] = d1; ss += d0 * d0 + d1 * d1; }
;                         ss += __shfl_xor(ss, 32);
;                         const float rstd = __builtin_amdgcn_rsqf(ss * (1.f / 128.f) + NORM_EPS) * (1.0f - lam_init);
; #pragma unroll
;                         for (int db = 0; db < 4; ++db)
; #pragma unroll
;                             for (int g = 0; g < 4; ++g) { const f32x4 gg = gld((const f32x4*)(dgain + 32 * db + 8 * g + 4 * hi));
; #pragma unroll
;                                 for (int e = 0; e < 4; ++e) o1[db][4 * g + e] *= gg[e]; }
	v_lshlrev_b32_e32 v3, 16, v169
	v_lshlrev_b32_e32 v2, 16, v168
	v_pk_fma_f32 v[34:35], v[0:1], v[18:19], v[6:7] op_sel_hi:[0,1,1] neg_lo:[1,0,0] neg_hi:[1,0,0]
	v_pk_fma_f32 v[32:33], v[0:1], v[8:9], v[2:3] op_sel_hi:[0,1,1] neg_lo:[1,0,0] neg_hi:[1,0,0]
	v_pk_mul_f32 v[2:3], v[34:35], v[34:35]
	v_and_b32_e32 v7, 0xffff0000, v167
	v_pk_fma_f32 v[2:3], v[32:33], v[32:33], v[2:3]
	v_and_b32_e32 v6, 0xffff0000, v166
	v_add_f32_e32 v1, v1, v2
	v_add_f32_e32 v1, v1, v3
	v_mov_b32_e32 v9, v22
	v_mov_b32_e32 v22, v21
	v_lshlrev_b32_e32 v3, 16, v167
	v_lshlrev_b32_e32 v2, 16, v166
	v_mov_b32_e32 v8, v20
	v_pk_fma_f32 v[18:19], v[0:1], v[22:23], v[6:7] op_sel_hi:[0,1,1] neg_lo:[1,0,0] neg_hi:[1,0,0]
	v_pk_fma_f32 v[16:17], v[0:1], v[8:9], v[2:3] op_sel_hi:[0,1,1] neg_lo:[1,0,0] neg_hi:[1,0,0]
	v_pk_mul_f32 v[2:3], v[18:19], v[18:19]
	v_and_b32_e32 v9, 0xffff0000, v165
	v_pk_fma_f32 v[2:3], v[16:17], v[16:17], v[2:3]
	v_and_b32_e32 v8, 0xffff0000, v164
	v_add_f32_e32 v1, v1, v2
	v_add_f32_e32 v1, v1, v3
	v_mov_b32_e32 v7, v26
	v_mov_b32_e32 v26, v25
	v_lshlrev_b32_e32 v3, 16, v165
	v_lshlrev_b32_e32 v2, 16, v164
	v_mov_b32_e32 v6, v24
	v_pk_fma_f32 v[8:9], v[0:1], v[26:27], v[8:9] op_sel_hi:[0,1,1] neg_lo:[1,0,0] neg_hi:[1,0,0]
	v_pk_fma_f32 v[6:7], v[0:1], v[6:7], v[2:3] op_sel_hi:[0,1,1] neg_lo:[1,0,0] neg_hi:[1,0,0]
	v_pk_mul_f32 v[2:3], v[8:9], v[8:9]
	v_mov_b32_e32 v13, v30
	v_pk_fma_f32 v[2:3], v[6:7], v[6:7], v[2:3]
	v_mov_b32_e32 v30, v29
	v_add_f32_e32 v1, v1, v2
	v_add_f32_e32 v10, v1, v3
	v_lshlrev_b32_e32 v3, 16, v163
	v_lshlrev_b32_e32 v2, 16, v162
	v_mov_b32_e32 v12, v28
	v_pk_fma_f32 v[14:15], v[0:1], v[30:31], v[14:15] op_sel_hi:[0,1,1] neg_lo:[1,0,0] neg_hi:[1,0,0]
	v_pk_fma_f32 v[12:13], v[0:1], v[12:13], v[2:3] op_sel_hi:[0,1,1] neg_lo:[1,0,0] neg_hi:[1,0,0]
	v_pk_mul_f32 v[0:1], v[14:15], v[14:15]
	s_lshl_b64 s[4:5], s[40:41], 21
	v_pk_fma_f32 v[0:1], v[12:13], v[12:13], v[0:1]
	v_readlane_b32 s7, v253, 62
	v_add_f32_e32 v0, v10, v0
	v_add_f32_e32 v0, v0, v1
	ds_bpermute_b32 v1, v174, v0
	s_add_u32 s4, s7, s4
	v_readlane_b32 s7, v251, 0
	s_addc_u32 s5, s7, s5
	s_lshl_b32 s6, s6, 1
	s_waitcnt lgkmcnt(0)
	v_add_f32_e32 v0, v0, v1
	v_fmamk_f32 v0, v0, 0x3c000000, v192
	v_rsq_f32_e32 v10, v0
	v_lshrrev_b32_e32 v0, 1, v175
	v_and_b32_e32 v92, 16, v0
	global_load_dwordx4 v[0:3], v92, s[42:43]
	global_load_dwordx4 v[22:25], v92, s[42:43] offset:32
	global_load_dwordx4 v[26:29], v92, s[42:43] offset:64
	global_load_dwordx4 v[36:39], v92, s[42:43] offset:96
	global_load_dwordx4 v[96:99], v92, s[42:43] offset:128
	global_load_dwordx4 v[100:103], v92, s[42:43] offset:160
	global_load_dwordx4 v[104:107], v92, s[42:43] offset:192
	global_load_dwordx4 v[108:111], v92, s[42:43] offset:224
	global_load_dwordx4 v[112:115], v92, s[42:43] offset:256
	global_load_dwordx4 v[116:119], v92, s[42:43] offset:288
	global_load_dwordx4 v[120:123], v92, s[42:43] offset:320
	global_load_dwordx4 v[124:127], v92, s[42:43] offset:352
	global_load_dwordx4 v[128:131], v92, s[42:43] offset:384
	global_load_dwordx4 v[132:135], v92, s[42:43] offset:416
	global_load_dwordx4 v[136:139], v92, s[42:43] offset:448
	global_load_dwordx4 v[140:143], v92, s[42:43] offset:480
	s_add_u32 s14, s4, s6
	s_addc_u32 s15, s5, 0
	s_waitcnt vmcnt(15)
	v_mul_f32_e32 v4, v0, v4
	s_waitcnt vmcnt(14)
	v_mul_f32_e32 v21, v22, v86
	v_mul_f32_e32 v22, v23, v87
	v_mul_f32_e32 v20, v25, v89
	s_waitcnt vmcnt(13)
	v_mul_f32_e32 v25, v26, v82
	v_mul_f32_e32 v26, v27, v83
	v_mul_f32_e32 v23, v28, v84
	s_waitcnt vmcnt(12)
	v_mul_f32_e32 v27, v38, v78
	v_mul_f32_e32 v28, v39, v79
	v_mul_f32_e32 v0, v3, v91
	v_mul_f32_e32 v3, v24, v88
	v_mul_f32_e32 v24, v29, v85
	v_mul_f32_e32 v29, v36, v80
	v_mul_f32_e32 v30, v37, v81
	v_mov_b32_e32 v153, v2
	v_mul_f32_e32 v1, v1, v90
	v_and_b32_e32 v2, 31, v175
	v_mul_u32_u24_e32 v2, 0x110, v2
	s_waitcnt vmcnt(11)
	v_mul_f32_e32 v37, v96, v74
	v_mul_f32_e32 v38, v97, v75
	v_mul_f32_e32 v31, v98, v76
	v_mul_f32_e32 v36, v99, v77
	s_waitcnt vmcnt(10)
	v_mul_f32_e32 v41, v100, v52
	v_mul_f32_e32 v42, v101, v71
	v_mul_f32_e32 v39, v102, v72
	v_mul_f32_e32 v40, v103, v73
	s_waitcnt vmcnt(9)
	v_mul_f32_e32 v52, v104, v50
	v_mul_f32_e32 v53, v105, v53
	v_mul_f32_e32 v50, v107, v70
	v_mul_f32_e32 v47, v106, v69
	s_waitcnt vmcnt(8)
	v_mul_f32_e32 v61, v108, v59
	v_mul_f32_e32 v62, v109, v60
	v_mul_f32_e32 v60, v111, v68
	v_mul_f32_e32 v59, v110, v67
	s_waitcnt vmcnt(7)
	v_mul_f32_e32 v67, v112, v63
	v_mul_f32_e32 v68, v113, v64
	v_mul_f32_e32 v63, v114, v65
	v_mul_f32_e32 v64, v115, v66
	s_waitcnt vmcnt(6)
	v_mul_f32_e32 v65, v116, v55
	v_mul_f32_e32 v66, v117, v56
	v_mul_f32_e32 v55, v118, v57
	v_mul_f32_e32 v56, v119, v58
	s_waitcnt vmcnt(5)
	v_mul_f32_e32 v57, v120, v48
	v_mul_f32_e32 v58, v121, v49
	v_mul_f32_e32 v48, v122, v51
	v_mul_f32_e32 v49, v123, v54
	s_waitcnt vmcnt(4)
	v_mul_f32_e32 v51, v124, v43
	v_mul_f32_e32 v54, v125, v44
	v_mul_f32_e32 v43, v126, v45
	v_mul_f32_e32 v44, v127, v46
	s_waitcnt vmcnt(3)
	v_mul_f32_e32 v45, v128, v32
	v_mul_f32_e32 v34, v129, v34
	v_mul_f32_e32 v32, v130, v33
	v_mul_f32_e32 v33, v131, v35
	s_waitcnt vmcnt(2)
	v_mul_f32_e32 v35, v132, v16
	v_mul_f32_e32 v18, v133, v18
	v_mul_f32_e32 v16, v134, v17
	v_mul_f32_e32 v17, v135, v19
	s_waitcnt vmcnt(1)
	v_mul_f32_e32 v19, v136, v6
	v_mul_f32_e32 v46, v137, v8
	v_mul_f32_e32 v69, v138, v7
	v_mul_f32_e32 v70, v139, v9
	s_waitcnt vmcnt(0)
; #define LAS __attribute__((address_space(3)))
; __device__ __forceinline__ unsigned cvt_pk_bf16(float lo, float hi) { unsigned r; asm volatile("v_cvt_pk_bf16_f32 %0, %1, %2" : "=v"(r) : "v"(lo), "v"(hi)); return r; }
; template <int DV>
; __device__ __forceinline__ void store_o(LAS unsigned char* lds, bf16_t* O, int pitchO, int rowbase, int wave, int t2, const f32x16 (&o)[DV / 32], float sc) {
;     ...
; #pragma unroll
;     for (int db = 0; db < DV / 32; ++db)
; #pragma unroll
;         for (int g = 0; g < 4; ++g) {
;             u32x2 w; w.x = cvt_pk_bf16(o[db][4 * g] * sc, o[db][4 * g + 1] * sc); w.y = cvt_pk_bf16(o[db][4 * g + 2] * sc, o[db][4 * g + 3] * sc);
;             *(LAS u32x2*)(st + r32 * PO + 64 * db + 16 * g + 8 * hi) = w;
;         }
; #pragma unroll
;     for (int i = 0; i < 32 * CH / 64; ++i) { const int id = lane + 64 * i, row = id / CH, ch = id % CH;
;         const u32x4 v = *(const LAS u32x4*)(st + row * PO + ch * 16);
;         gst((u32x4*)(O + (size_t)(rowbase + row) * pitchO + ch * 8), v); }
; __global__ void __launch_bounds__(512, 2) mega(Args a) {
;     ...
; #pragma unroll
;                         for (int db = 0; db < 4; ++db)
; #pragma unroll
;                             for (int g = 0; g < 4; ++g) { const f32x4 gg = gld((const f32x4*)(dgain + 32 * db + 8 * g + 4 * hi));
; #pragma unroll
;                                 for (int e = 0; e < 4; ++e) o1[db][4 * g + e] *= gg[e]; }
	v_mul_f32_e32 v12, v140, v12
	v_mul_f32_e32 v14, v141, v14
	v_mul_f32_e32 v13, v142, v13
	v_pk_mul_f32 v[6:7], v[152:153], v[10:11]
	v_lshrrev_b32_e32 v8, 2, v175
	v_and_b32_e32 v8, 8, v8
	v_mul_f32_e32 v1, v6, v1
	v_add3_u32 v2, s71, v2, v8
	v_mul_f32_e32 v4, v6, v4
	v_cvt_pk_bf16_f32 v8, v4, v1
	v_mul_f32_e32 v1, v6, v7
	v_mul_f32_e32 v0, v6, v0
	v_mul_f32_e32 v15, v143, v15
	v_cvt_pk_bf16_f32 v9, v1, v0
	v_mul_f32_e32 v0, v6, v21
	v_mul_f32_e32 v1, v6, v22
	ds_write_b64 v2, v[8:9]
	v_cvt_pk_bf16_f32 v0, v0, v1
	v_mul_f32_e32 v1, v6, v3
	v_mul_f32_e32 v3, v6, v20
	v_cvt_pk_bf16_f32 v1, v1, v3
	ds_write_b64 v2, v[0:1] offset:16
	v_mul_f32_e32 v0, v6, v25
	v_mul_f32_e32 v1, v6, v26
	v_cvt_pk_bf16_f32 v0, v0, v1
	v_mul_f32_e32 v1, v6, v23
	v_mul_f32_e32 v3, v6, v24
	v_cvt_pk_bf16_f32 v1, v1, v3
	ds_write_b64 v2, v[0:1] offset:32
	v_mul_f32_e32 v0, v6, v29
	v_mul_f32_e32 v1, v6, v30
	v_cvt_pk_bf16_f32 v0, v0, v1
	v_mul_f32_e32 v1, v6, v27
	v_mul_f32_e32 v3, v6, v28
	v_cvt_pk_bf16_f32 v1, v1, v3
	ds_write_b64 v2, v[0:1] offset:48
	v_mul_f32_e32 v0, v6, v37
	v_mul_f32_e32 v1, v6, v38
	v_cvt_pk_bf16_f32 v0, v0, v1
	v_mul_f32_e32 v1, v6, v31
	v_mul_f32_e32 v3, v6, v36
	v_cvt_pk_bf16_f32 v1, v1, v3
	ds_write_b64 v2, v[0:1] offset:64
	v_mul_f32_e32 v0, v6, v41
	v_mul_f32_e32 v1, v6, v42
	v_cvt_pk_bf16_f32 v0, v0, v1
	v_mul_f32_e32 v1, v6, v39
	v_mul_f32_e32 v3, v6, v40
	v_cvt_pk_bf16_f32 v1, v1, v3
	ds_write_b64 v2, v[0:1] offset:80
	v_mul_f32_e32 v0, v6, v52
	v_mul_f32_e32 v1, v6, v53
	v_cvt_pk_bf16_f32 v0, v0, v1
	v_mul_f32_e32 v1, v6, v47
	v_mul_f32_e32 v3, v6, v50
	v_cvt_pk_bf16_f32 v1, v1, v3
	ds_write_b64 v2, v[0:1] offset:96
	v_mul_f32_e32 v0, v6, v61
	v_mul_f32_e32 v1, v6, v62
	v_cvt_pk_bf16_f32 v0, v0, v1
	v_mul_f32_e32 v1, v6, v59
	v_mul_f32_e32 v3, v6, v60
	v_cvt_pk_bf16_f32 v1, v1, v3
	ds_write_b64 v2, v[0:1] offset:112
	v_mul_f32_e32 v0, v6, v67
	v_mul_f32_e32 v1, v6, v68
	v_cvt_pk_bf16_f32 v0, v0, v1
	v_mul_f32_e32 v1, v6, v63
	v_mul_f32_e32 v3, v6, v64
	v_cvt_pk_bf16_f32 v1, v1, v3
	ds_write_b64 v2, v[0:1] offset:128
	v_mul_f32_e32 v0, v6, v65
	v_mul_f32_e32 v1, v6, v66
	v_cvt_pk_bf16_f32 v0, v0, v1
	v_mul_f32_e32 v1, v6, v55
	v_mul_f32_e32 v3, v6, v56
	v_cvt_pk_bf16_f32 v1, v1, v3
	ds_write_b64 v2, v[0:1] offset:144
	v_mul_f32_e32 v0, v6, v57
	v_mul_f32_e32 v1, v6, v58
	v_cvt_pk_bf16_f32 v0, v0, v1
	v_mul_f32_e32 v1, v6, v48
	v_mul_f32_e32 v3, v6, v49
	v_cvt_pk_bf16_f32 v1, v1, v3
	ds_write_b64 v2, v[0:1] offset:160
	v_mul_f32_e32 v0, v6, v51
	v_mul_f32_e32 v1, v6, v54
	v_cvt_pk_bf16_f32 v0, v0, v1
	v_mul_f32_e32 v1, v6, v43
	v_mul_f32_e32 v3, v6, v44
	v_cvt_pk_bf16_f32 v1, v1, v3
	ds_write_b64 v2, v[0:1] offset:176
	v_mul_f32_e32 v0, v6, v45
	v_mul_f32_e32 v1, v6, v34
	v_cvt_pk_bf16_f32 v0, v0, v1
	v_mul_f32_e32 v1, v6, v32
	v_mul_f32_e32 v3, v6, v33
	v_cvt_pk_bf16_f32 v1, v1, v3
	ds_write_b64 v2, v[0:1] offset:192
	v_mul_f32_e32 v0, v6, v35
	v_mul_f32_e32 v1, v6, v18
	v_cvt_pk_bf16_f32 v0, v0, v1
	v_mul_f32_e32 v1, v6, v16
	v_mul_f32_e32 v3, v6, v17
	v_cvt_pk_bf16_f32 v1, v1, v3
	ds_write_b64 v2, v[0:1] offset:208
	v_mul_f32_e32 v0, v6, v19
	v_mul_f32_e32 v1, v6, v46
	v_cvt_pk_bf16_f32 v0, v0, v1
	v_mul_f32_e32 v1, v6, v69
	v_mul_f32_e32 v3, v6, v70
	v_cvt_pk_bf16_f32 v1, v1, v3
	ds_write_b64 v2, v[0:1] offset:224
	v_mul_f32_e32 v0, v6, v12
	v_mul_f32_e32 v1, v6, v14
	v_cvt_pk_bf16_f32 v0, v0, v1
	v_mul_f32_e32 v1, v6, v13
	v_mul_f32_e32 v3, v6, v15
	v_cvt_pk_bf16_f32 v1, v1, v3
	ds_write_b64 v2, v[0:1] offset:240
	v_lshlrev_b32_e32 v0, 4, v175
	v_bfe_u32 v12, v175, 4, 2
	v_and_b32_e32 v4, 0xf0, v0
	v_mul_u32_u24_e32 v2, 0x110, v12
	v_lshl_add_u64 v[0:1], s[14:15], 0, v[4:5]
	v_add3_u32 v4, s71, v4, v2
	ds_read_b128 v[6:9], v4
	v_or_b32_e32 v2, s61, v12
	v_ashrrev_i32_e32 v3, 31, v2
	v_lshlrev_b64 v[10:11], 10, v[2:3]
	v_lshl_add_u64 v[10:11], v[0:1], 0, v[10:11]
	s_waitcnt lgkmcnt(0)
	global_store_dwordx4 v[10:11], v[6:9], off
	ds_read_b128 v[6:9], v4 offset:1088
	v_or_b32_e32 v10, 4, v2
	v_ashrrev_i32_e32 v11, 31, v10
	v_lshlrev_b64 v[10:11], 10, v[10:11]
	v_lshl_add_u64 v[10:11], v[0:1], 0, v[10:11]
	s_waitcnt lgkmcnt(0)
	global_store_dwordx4 v[10:11], v[6:9], off
	ds_read_b128 v[6:9], v4 offset:2176
	v_or_b32_e32 v10, 8, v2
	v_ashrrev_i32_e32 v11, 31, v10
	v_lshlrev_b64 v[10:11], 10, v[10:11]
	v_lshl_add_u64 v[10:11], v[0:1], 0, v[10:11]
	s_waitcnt lgkmcnt(0)
	global_store_dwordx4 v[10:11], v[6:9], off
	ds_read_b128 v[6:9], v4 offset:3264
	v_or_b32_e32 v10, 12, v2
	v_ashrrev_i32_e32 v11, 31, v10
	v_lshlrev_b64 v[10:11], 10, v[10:11]
	v_lshl_add_u64 v[10:11], v[0:1], 0, v[10:11]
	s_waitcnt lgkmcnt(0)
	global_store_dwordx4 v[10:11], v[6:9], off
	ds_read_b128 v[6:9], v4 offset:4352
	v_or_b32_e32 v10, 16, v2
	v_ashrrev_i32_e32 v11, 31, v10
	v_lshlrev_b64 v[10:11], 10, v[10:11]
	v_lshl_add_u64 v[10:11], v[0:1], 0, v[10:11]
	s_waitcnt lgkmcnt(0)
	global_store_dwordx4 v[10:11], v[6:9], off
	ds_read_b128 v[6:9], v4 offset:5440
	v_or_b32_e32 v10, 20, v2
	v_ashrrev_i32_e32 v11, 31, v10
	v_lshlrev_b64 v[10:11], 10, v[10:11]
	v_lshl_add_u64 v[10:11], v[0:1], 0, v[10:11]
	s_waitcnt lgkmcnt(0)
	global_store_dwordx4 v[10:11], v[6:9], off
	ds_read_b128 v[6:9], v4 offset:6528
	v_or_b32_e32 v2, 24, v2
	v_ashrrev_i32_e32 v3, 31, v2
	v_lshlrev_b64 v[2:3], 10, v[2:3]
	v_lshl_add_u64 v[2:3], v[0:1], 0, v[2:3]
	s_waitcnt lgkmcnt(0)
	global_store_dwordx4 v[2:3], v[6:9], off
	v_or_b32_e32 v3, 28, v12
	v_add_u32_e32 v2, 0x1dc0, v4
